# v9 plus attention unit order per workgroup 63-s, s, 32+s, 31-s (K/V tile streams of the 16 workgroups sharing a head re-synchronise after each pair)
# baseline (speedup 1.0000x reference)
; __device__ __forceinline__ int phase_tid(int wave0) { int t; asm volatile("v_mbcnt_lo_u32_b32 %0, -1, 0\n\tv_mbcnt_hi_u32_b32 %0, -1, %0" : "=v"(t)); return t | (wave0 << 6); }
; __global__ void __launch_bounds__(512, 2) mega(Args args) {
;     ...
;                     const int v = vcu, bh = v >> 4, s = v & 15;
; #pragma unroll 1
;                     for (int i = 0; i < 4; ++i) { const int qb = (i == 0) ? 63 - s : (i == 1) ? 32 + s : (i == 2) ? 31 - s : s;
;                         if (ac.Mfix <= 40.f) diff_attn_unit<true>(lds, proj, VT, bh >> 3, bh & 7, qb, ac, gsub, phase_tid(wave0), real ? proj : mg, real ? NP : DM, real ? C_OB : 0);
;                         else diff_attn_unit<false>(lds, proj, VT, bh >> 3, bh & 7, qb, ac, gsub, phase_tid(wave0), real ? proj : mg, real ? NP : DM, real ? C_OB : 0); }
.LBB1_269:
	s_cmp_lt_i32 s61, 1
	s_mov_b32 s84, s56
	s_cbranch_scc1 .LBB1_274
	s_cmp_lg_u32 s61, 1
	s_mov_b64 s[70:71], -1
	s_cbranch_scc0 .LBB1_272
	s_cmp_eq_u32 s61, 2
	s_cselect_b32 s84, s22, s23
	s_mov_b64 s[70:71], 0
.LBB1_272:
	s_andn2_b64 vcc, exec, s[70:71]
	s_cbranch_vccnz .LBB1_274
	s_mov_b32 s84, s46
